# K-loops: per-phase s_setprio flips removed; one static s_setprio 1 for waves 0-3 (the leading half) at kernel entry
# baseline (speedup 1.0000x reference)
; #define LAS __attribute__((address_space(3)))
; #define REP(k) for (int rep_ = 0; rep_ < 1 + ((k) == PROBE_REP_PHASE ? PROBE_REP_N : 0); ++rep_)
; __global__ void __launch_bounds__(512, 2) mk_fwd(Args args) {
;     extern __shared__ __attribute__((aligned(16))) unsigned char lds_raw[];
;     Frame F;
;     F.lds = (LAS unsigned char*)lds_raw;
;     F.tid = threadIdx.x; F.lane = F.tid & 63; F.wave = __builtin_amdgcn_readfirstlane(F.tid >> 6); F.G = gridDim.x; F.bid = blockIdx.x;
; #pragma unroll
;     for (int i = 0; i < 23; ++i) F.in[i] = args.in[i];
;     F.out = args.out; F.ws = args.ws;
;     volatile LAS unsigned* MISC = (volatile LAS unsigned*)(F.lds + MISC_OFF);
;     if (F.tid < 32) MISC[F.tid] = 0u;
;     __syncthreads();
;     XcdBarrier bar; bar.bar = (unsigned*)(F.ws + WS_CTL) + CW_BAR; bar.x = 0; bar.st = nullptr;
;     ...
;     const int lo = args.ph_lo, hi = args.ph_hi;
;     ...
;     unsigned long long pt0 = (PROBE_T_LO == 0) ? __builtin_amdgcn_s_memrealtime() : 0ull, pt1 = 0ull;
;     unsigned char* ws = F.ws; const float* mod = (const float*)(ws + WS_MOD);
;     if (IN(0)) REP(0) { phase_prep(F); }
.LBB0_5:
	s_or_b64 exec, exec, s[4:5]
	s_load_dwordx16 s[36:51], s[0:1], 0x0
	s_load_dwordx16 s[68:83], s[0:1], 0x40
	s_load_dwordx2 s[26:27], s[0:1], 0xc8
	s_load_dwordx16 s[4:19], s[0:1], 0x80
	s_lshr_b32 s0, s86, 6
	s_cmp_lt_u32 s0, 4
	s_cbranch_scc0 .Lprio_skip
	s_setprio 1
.Lprio_skip:
	v_and_b32_e32 v209, 63, v0
	s_waitcnt lgkmcnt(0)
	v_writelane_b32 v253, s4, 7
	s_nop 1
	v_writelane_b32 v253, s5, 8
	v_writelane_b32 v253, s6, 9
	v_writelane_b32 v253, s7, 10
	v_writelane_b32 v253, s8, 11
	v_writelane_b32 v253, s9, 12
	v_writelane_b32 v253, s10, 13
	v_writelane_b32 v253, s11, 14
	v_writelane_b32 v253, s12, 15
	v_writelane_b32 v253, s13, 16
	v_writelane_b32 v253, s14, 17
	v_writelane_b32 v253, s15, 18
	v_writelane_b32 v253, s16, 19
	v_writelane_b32 v253, s17, 20
	v_writelane_b32 v253, s18, 21
	v_writelane_b32 v253, s19, 22
	v_writelane_b32 v253, s0, 23
	s_add_u32 s0, s56, 0x100000
	s_addc_u32 s1, s57, 0
	v_writelane_b32 v253, s0, 24
	s_cmp_lt_i32 s26, 1
	s_nop 0
	v_writelane_b32 v253, s1, 25
	v_writelane_b32 v253, s36, 26
	s_cselect_b64 s[0:1], -1, 0
	s_cmp_gt_i32 s27, 0
	v_writelane_b32 v253, s37, 27
	v_writelane_b32 v253, s38, 28
	v_writelane_b32 v253, s39, 29
	v_writelane_b32 v253, s40, 30
	v_writelane_b32 v253, s41, 31
	v_writelane_b32 v253, s42, 32
	v_writelane_b32 v253, s43, 33
	v_writelane_b32 v253, s44, 34
	v_writelane_b32 v253, s45, 35
	v_writelane_b32 v253, s46, 36
	v_writelane_b32 v253, s47, 37
	v_writelane_b32 v253, s48, 38
	v_writelane_b32 v253, s49, 39
	s_cselect_b64 s[2:3], -1, 0
	v_writelane_b32 v253, s50, 40
	s_and_b64 s[0:1], s[0:1], s[2:3]
	v_writelane_b32 v253, s51, 41
	s_andn2_b64 vcc, exec, s[0:1]
	v_writelane_b32 v253, s26, 42
	s_nop 1
	v_writelane_b32 v253, s27, 43
	s_cbranch_vccnz .LBB0_72
	v_mov_b32_e32 v5, 0
	v_lshlrev_b32_e32 v2, 2, v0
	v_mov_b32_e32 v3, v5
	v_lshl_add_u64 v[6:7], s[38:39], 0, v[2:3]
	v_add_u32_e32 v1, 0, v2
	s_mov_b64 s[0:1], 0
	s_movk_i32 s2, 0x800
	s_mov_b64 s[4:5], 0x800
	s_movk_i32 s3, 0x9ff
	v_mov_b32_e32 v3, v0
